# V plane re-laid as per-tile transposed images by an extra pass + grid barrier; attention reads V fragments with ds_read_b128 (32 LDS reads per tile instead of 64)
# baseline (speedup 1.0000x reference)
.LBB0_248:
	s_or_b64 exec, exec, s[0:1]
	s_waitcnt lgkmcnt(0)
	s_barrier
	v_mbcnt_lo_u32_b32 v60, -1, 0
	v_mbcnt_hi_u32_b32 v60, -1, v60
	s_add_u32 s4, s66, 0x20200000
	s_addc_u32 s5, s67, 0
	s_lshl_b32 s6, s88, 19
	s_add_u32 s4, s4, s6
	s_addc_u32 s5, s5, 0
	s_lshl_b32 s6, s89, 6
	s_add_u32 s4, s4, s6
	s_addc_u32 s5, s5, 0
	s_lshl_b32 s8, s88, 15
	s_add_u32 s6, s64, s8
	s_addc_u32 s7, s65, 0
	s_lshl_b32 s8, s89, 12
	s_add_u32 s6, s6, s8
	s_addc_u32 s7, s7, 0
	v_lshrrev_b32_e32 v61, 2, v60
	v_and_b32_e32 v62, 3, v60
	v_lshlrev_b32_e32 v48, 13, v61
	v_lshl_add_u32 v48, v62, 4, v48
	v_add_u32_e32 v49, 0x20000, v48
	v_add_u32_e32 v50, 0x40000, v48
	v_add_u32_e32 v51, 0x60000, v48
	v_lshlrev_b32_e32 v52, 6, v61
	v_lshl_add_u32 v52, v62, 4, v52
	v_add_u32_e32 v52, s8, v52
	v_lshrrev_b32_e32 v53, 4, v60
	v_and_b32_e32 v54, 15, v60
	v_lshrrev_b32_e32 v55, 2, v54
	v_lshl_add_u32 v55, v53, 2, v55
	v_lshlrev_b32_e32 v55, 6, v55
	v_and_b32_e32 v56, 3, v54
	v_lshl_add_u32 v55, v56, 3, v55
	v_add_u32_e32 v55, s8, v55
	v_and_b32_e32 v56, 7, v54
	v_lshrrev_b32_e32 v58, 3, v54
	v_xor_b32_e32 v56, v56, v58
	v_xor_b32_e32 v56, v53, v56
	v_lshlrev_b32_e32 v56, 4, v56
	v_lshl_add_u32 v56, v54, 7, v56
	v_xor_b32_e32 v57, 64, v56
	global_load_dwordx4 v[0:3], v48, s[4:5]
	global_load_dwordx4 v[4:7], v49, s[4:5]
	global_load_dwordx4 v[8:11], v50, s[4:5]
	global_load_dwordx4 v[12:15], v51, s[4:5]
	s_add_u32 s4, s4, 0x200
	s_addc_u32 s5, s5, 0
	global_load_dwordx4 v[32:35], v48, s[4:5]
	global_load_dwordx4 v[36:39], v49, s[4:5]
	global_load_dwordx4 v[40:43], v50, s[4:5]
	global_load_dwordx4 v[44:47], v51, s[4:5]
	s_add_u32 s4, s4, 0x200
	s_addc_u32 s5, s5, 0
	s_waitcnt vmcnt(4)
	ds_write_b128 v52, v[0:3]
	ds_write_b128 v52, v[4:7] offset:1024
	ds_write_b128 v52, v[8:11] offset:2048
	ds_write_b128 v52, v[12:15] offset:3072
	s_waitcnt lgkmcnt(0)
	ds_read_b64_tr_b16 v[16:17], v55
	ds_read_b64_tr_b16 v[18:19], v55 offset:1024
	ds_read_b64_tr_b16 v[20:21], v55 offset:32
	ds_read_b64_tr_b16 v[22:23], v55 offset:1056
	ds_read_b64_tr_b16 v[24:25], v55 offset:2048
	ds_read_b64_tr_b16 v[26:27], v55 offset:3072
	ds_read_b64_tr_b16 v[28:29], v55 offset:2080
	ds_read_b64_tr_b16 v[30:31], v55 offset:3104
	s_waitcnt lgkmcnt(0)
	global_store_dwordx4 v56, v[16:19], s[6:7]
	global_store_dwordx4 v56, v[20:23], s[6:7] offset:2048
	global_store_dwordx4 v57, v[24:27], s[6:7]
	global_store_dwordx4 v57, v[28:31], s[6:7] offset:2048
	s_add_u32 s6, s6, 0x800000
	s_addc_u32 s7, s7, 0
	global_load_dwordx4 v[0:3], v48, s[4:5]
	global_load_dwordx4 v[4:7], v49, s[4:5]
	global_load_dwordx4 v[8:11], v50, s[4:5]
	global_load_dwordx4 v[12:15], v51, s[4:5]
	s_add_u32 s4, s4, 0x200
	s_addc_u32 s5, s5, 0
	s_waitcnt vmcnt(8)
	ds_write_b128 v52, v[32:35]
	ds_write_b128 v52, v[36:39] offset:1024
	ds_write_b128 v52, v[40:43] offset:2048
	ds_write_b128 v52, v[44:47] offset:3072
	s_waitcnt lgkmcnt(0)
	ds_read_b64_tr_b16 v[16:17], v55
	ds_read_b64_tr_b16 v[18:19], v55 offset:1024
	ds_read_b64_tr_b16 v[20:21], v55 offset:32
	ds_read_b64_tr_b16 v[22:23], v55 offset:1056
	ds_read_b64_tr_b16 v[24:25], v55 offset:2048
	ds_read_b64_tr_b16 v[26:27], v55 offset:3072
	ds_read_b64_tr_b16 v[28:29], v55 offset:2080
	ds_read_b64_tr_b16 v[30:31], v55 offset:3104
	s_waitcnt lgkmcnt(0)
	global_store_dwordx4 v56, v[16:19], s[6:7]
	global_store_dwordx4 v56, v[20:23], s[6:7] offset:2048
	global_store_dwordx4 v57, v[24:27], s[6:7]
	global_store_dwordx4 v57, v[28:31], s[6:7] offset:2048
	s_add_u32 s6, s6, 0x800000
	s_addc_u32 s7, s7, 0
	global_load_dwordx4 v[32:35], v48, s[4:5]
	global_load_dwordx4 v[36:39], v49, s[4:5]
	global_load_dwordx4 v[40:43], v50, s[4:5]
	global_load_dwordx4 v[44:47], v51, s[4:5]
	s_add_u32 s4, s4, 0x200
	s_addc_u32 s5, s5, 0
	s_waitcnt vmcnt(8)
	ds_write_b128 v52, v[0:3]
	ds_write_b128 v52, v[4:7] offset:1024
	ds_write_b128 v52, v[8:11] offset:2048
	ds_write_b128 v52, v[12:15] offset:3072
	s_waitcnt lgkmcnt(0)
	ds_read_b64_tr_b16 v[16:17], v55
	ds_read_b64_tr_b16 v[18:19], v55 offset:1024
	ds_read_b64_tr_b16 v[20:21], v55 offset:32
	ds_read_b64_tr_b16 v[22:23], v55 offset:1056
	ds_read_b64_tr_b16 v[24:25], v55 offset:2048
	ds_read_b64_tr_b16 v[26:27], v55 offset:3072
	ds_read_b64_tr_b16 v[28:29], v55 offset:2080
	ds_read_b64_tr_b16 v[30:31], v55 offset:3104
	s_waitcnt lgkmcnt(0)
	global_store_dwordx4 v56, v[16:19], s[6:7]
	global_store_dwordx4 v56, v[20:23], s[6:7] offset:2048
	global_store_dwordx4 v57, v[24:27], s[6:7]
	global_store_dwordx4 v57, v[28:31], s[6:7] offset:2048
	s_add_u32 s6, s6, 0x800000
	s_addc_u32 s7, s7, 0
	global_load_dwordx4 v[0:3], v48, s[4:5]
	global_load_dwordx4 v[4:7], v49, s[4:5]
	global_load_dwordx4 v[8:11], v50, s[4:5]
	global_load_dwordx4 v[12:15], v51, s[4:5]
	s_add_u32 s4, s4, 0x200
	s_addc_u32 s5, s5, 0
	s_waitcnt vmcnt(8)
	ds_write_b128 v52, v[32:35]
	ds_write_b128 v52, v[36:39] offset:1024
	ds_write_b128 v52, v[40:43] offset:2048
	ds_write_b128 v52, v[44:47] offset:3072
	s_waitcnt lgkmcnt(0)
	ds_read_b64_tr_b16 v[16:17], v55
	ds_read_b64_tr_b16 v[18:19], v55 offset:1024
	ds_read_b64_tr_b16 v[20:21], v55 offset:32
	ds_read_b64_tr_b16 v[22:23], v55 offset:1056
	ds_read_b64_tr_b16 v[24:25], v55 offset:2048
	ds_read_b64_tr_b16 v[26:27], v55 offset:3072
	ds_read_b64_tr_b16 v[28:29], v55 offset:2080
	ds_read_b64_tr_b16 v[30:31], v55 offset:3104
	s_waitcnt lgkmcnt(0)
	global_store_dwordx4 v56, v[16:19], s[6:7]
	global_store_dwordx4 v56, v[20:23], s[6:7] offset:2048
	global_store_dwordx4 v57, v[24:27], s[6:7]
	global_store_dwordx4 v57, v[28:31], s[6:7] offset:2048
	s_add_u32 s6, s6, 0x800000
	s_addc_u32 s7, s7, 0
	global_load_dwordx4 v[32:35], v48, s[4:5]
	global_load_dwordx4 v[36:39], v49, s[4:5]
	global_load_dwordx4 v[40:43], v50, s[4:5]
	global_load_dwordx4 v[44:47], v51, s[4:5]
	s_add_u32 s4, s4, 0x200
	s_addc_u32 s5, s5, 0
	s_waitcnt vmcnt(8)
	ds_write_b128 v52, v[0:3]
	ds_write_b128 v52, v[4:7] offset:1024
	ds_write_b128 v52, v[8:11] offset:2048
	ds_write_b128 v52, v[12:15] offset:3072
	s_waitcnt lgkmcnt(0)
	ds_read_b64_tr_b16 v[16:17], v55
	ds_read_b64_tr_b16 v[18:19], v55 offset:1024
	ds_read_b64_tr_b16 v[20:21], v55 offset:32
	ds_read_b64_tr_b16 v[22:23], v55 offset:1056
	ds_read_b64_tr_b16 v[24:25], v55 offset:2048
	ds_read_b64_tr_b16 v[26:27], v55 offset:3072
	ds_read_b64_tr_b16 v[28:29], v55 offset:2080
	ds_read_b64_tr_b16 v[30:31], v55 offset:3104
	s_waitcnt lgkmcnt(0)
	global_store_dwordx4 v56, v[16:19], s[6:7]
	global_store_dwordx4 v56, v[20:23], s[6:7] offset:2048
	global_store_dwordx4 v57, v[24:27], s[6:7]
	global_store_dwordx4 v57, v[28:31], s[6:7] offset:2048
	s_add_u32 s6, s6, 0x800000
	s_addc_u32 s7, s7, 0
	global_load_dwordx4 v[0:3], v48, s[4:5]
	global_load_dwordx4 v[4:7], v49, s[4:5]
	global_load_dwordx4 v[8:11], v50, s[4:5]
	global_load_dwordx4 v[12:15], v51, s[4:5]
	s_add_u32 s4, s4, 0x200
	s_addc_u32 s5, s5, 0
	s_waitcnt vmcnt(8)
	ds_write_b128 v52, v[32:35]
	ds_write_b128 v52, v[36:39] offset:1024
	ds_write_b128 v52, v[40:43] offset:2048
	ds_write_b128 v52, v[44:47] offset:3072
	s_waitcnt lgkmcnt(0)
	ds_read_b64_tr_b16 v[16:17], v55
	ds_read_b64_tr_b16 v[18:19], v55 offset:1024
	ds_read_b64_tr_b16 v[20:21], v55 offset:32
	ds_read_b64_tr_b16 v[22:23], v55 offset:1056
	ds_read_b64_tr_b16 v[24:25], v55 offset:2048
	ds_read_b64_tr_b16 v[26:27], v55 offset:3072
	ds_read_b64_tr_b16 v[28:29], v55 offset:2080
	ds_read_b64_tr_b16 v[30:31], v55 offset:3104
	s_waitcnt lgkmcnt(0)
	global_store_dwordx4 v56, v[16:19], s[6:7]
	global_store_dwordx4 v56, v[20:23], s[6:7] offset:2048
	global_store_dwordx4 v57, v[24:27], s[6:7]
	global_store_dwordx4 v57, v[28:31], s[6:7] offset:2048
	s_add_u32 s6, s6, 0x800000
	s_addc_u32 s7, s7, 0
	global_load_dwordx4 v[32:35], v48, s[4:5]
	global_load_dwordx4 v[36:39], v49, s[4:5]
	global_load_dwordx4 v[40:43], v50, s[4:5]
	global_load_dwordx4 v[44:47], v51, s[4:5]
	s_add_u32 s4, s4, 0x200
	s_addc_u32 s5, s5, 0
	s_waitcnt vmcnt(8)
	ds_write_b128 v52, v[0:3]
	ds_write_b128 v52, v[4:7] offset:1024
	ds_write_b128 v52, v[8:11] offset:2048
	ds_write_b128 v52, v[12:15] offset:3072
	s_waitcnt lgkmcnt(0)
	ds_read_b64_tr_b16 v[16:17], v55
	ds_read_b64_tr_b16 v[18:19], v55 offset:1024
	ds_read_b64_tr_b16 v[20:21], v55 offset:32
	ds_read_b64_tr_b16 v[22:23], v55 offset:1056
	ds_read_b64_tr_b16 v[24:25], v55 offset:2048
	ds_read_b64_tr_b16 v[26:27], v55 offset:3072
	ds_read_b64_tr_b16 v[28:29], v55 offset:2080
	ds_read_b64_tr_b16 v[30:31], v55 offset:3104
	s_waitcnt lgkmcnt(0)
	global_store_dwordx4 v56, v[16:19], s[6:7]
	global_store_dwordx4 v56, v[20:23], s[6:7] offset:2048
	global_store_dwordx4 v57, v[24:27], s[6:7]
	global_store_dwordx4 v57, v[28:31], s[6:7] offset:2048
	s_add_u32 s6, s6, 0x800000
	s_addc_u32 s7, s7, 0
	global_load_dwordx4 v[0:3], v48, s[4:5]
	global_load_dwordx4 v[4:7], v49, s[4:5]
	global_load_dwordx4 v[8:11], v50, s[4:5]
	global_load_dwordx4 v[12:15], v51, s[4:5]
	s_add_u32 s4, s4, 0x200
	s_addc_u32 s5, s5, 0
	s_waitcnt vmcnt(8)
	ds_write_b128 v52, v[32:35]
	ds_write_b128 v52, v[36:39] offset:1024
	ds_write_b128 v52, v[40:43] offset:2048
	ds_write_b128 v52, v[44:47] offset:3072
	s_waitcnt lgkmcnt(0)
	ds_read_b64_tr_b16 v[16:17], v55
	ds_read_b64_tr_b16 v[18:19], v55 offset:1024
	ds_read_b64_tr_b16 v[20:21], v55 offset:32
	ds_read_b64_tr_b16 v[22:23], v55 offset:1056
	ds_read_b64_tr_b16 v[24:25], v55 offset:2048
	ds_read_b64_tr_b16 v[26:27], v55 offset:3072
	ds_read_b64_tr_b16 v[28:29], v55 offset:2080
	ds_read_b64_tr_b16 v[30:31], v55 offset:3104
	s_waitcnt lgkmcnt(0)
	global_store_dwordx4 v56, v[16:19], s[6:7]
	global_store_dwordx4 v56, v[20:23], s[6:7] offset:2048
	global_store_dwordx4 v57, v[24:27], s[6:7]
	global_store_dwordx4 v57, v[28:31], s[6:7] offset:2048
	s_add_u32 s6, s6, 0x800000
	s_addc_u32 s7, s7, 0
	global_load_dwordx4 v[32:35], v48, s[4:5]
	global_load_dwordx4 v[36:39], v49, s[4:5]
	global_load_dwordx4 v[40:43], v50, s[4:5]
	global_load_dwordx4 v[44:47], v51, s[4:5]
	s_add_u32 s4, s4, 0x200
	s_addc_u32 s5, s5, 0
	s_waitcnt vmcnt(8)
	ds_write_b128 v52, v[0:3]
	ds_write_b128 v52, v[4:7] offset:1024
	ds_write_b128 v52, v[8:11] offset:2048
	ds_write_b128 v52, v[12:15] offset:3072
	s_waitcnt lgkmcnt(0)
	ds_read_b64_tr_b16 v[16:17], v55
	ds_read_b64_tr_b16 v[18:19], v55 offset:1024
	ds_read_b64_tr_b16 v[20:21], v55 offset:32
	ds_read_b64_tr_b16 v[22:23], v55 offset:1056
	ds_read_b64_tr_b16 v[24:25], v55 offset:2048
	ds_read_b64_tr_b16 v[26:27], v55 offset:3072
	ds_read_b64_tr_b16 v[28:29], v55 offset:2080
	ds_read_b64_tr_b16 v[30:31], v55 offset:3104
	s_waitcnt lgkmcnt(0)
	global_store_dwordx4 v56, v[16:19], s[6:7]
	global_store_dwordx4 v56, v[20:23], s[6:7] offset:2048
	global_store_dwordx4 v57, v[24:27], s[6:7]
	global_store_dwordx4 v57, v[28:31], s[6:7] offset:2048
	s_add_u32 s6, s6, 0x800000
	s_addc_u32 s7, s7, 0
	global_load_dwordx4 v[0:3], v48, s[4:5]
	global_load_dwordx4 v[4:7], v49, s[4:5]
	global_load_dwordx4 v[8:11], v50, s[4:5]
	global_load_dwordx4 v[12:15], v51, s[4:5]
	s_add_u32 s4, s4, 0x200
	s_addc_u32 s5, s5, 0
	s_waitcnt vmcnt(8)
	ds_write_b128 v52, v[32:35]
	ds_write_b128 v52, v[36:39] offset:1024
	ds_write_b128 v52, v[40:43] offset:2048
	ds_write_b128 v52, v[44:47] offset:3072
	s_waitcnt lgkmcnt(0)
	ds_read_b64_tr_b16 v[16:17], v55
	ds_read_b64_tr_b16 v[18:19], v55 offset:1024
	ds_read_b64_tr_b16 v[20:21], v55 offset:32
	ds_read_b64_tr_b16 v[22:23], v55 offset:1056
	ds_read_b64_tr_b16 v[24:25], v55 offset:2048
	ds_read_b64_tr_b16 v[26:27], v55 offset:3072
	ds_read_b64_tr_b16 v[28:29], v55 offset:2080
	ds_read_b64_tr_b16 v[30:31], v55 offset:3104
	s_waitcnt lgkmcnt(0)
	global_store_dwordx4 v56, v[16:19], s[6:7]
	global_store_dwordx4 v56, v[20:23], s[6:7] offset:2048
	global_store_dwordx4 v57, v[24:27], s[6:7]
	global_store_dwordx4 v57, v[28:31], s[6:7] offset:2048
	s_add_u32 s6, s6, 0x800000
	s_addc_u32 s7, s7, 0
	global_load_dwordx4 v[32:35], v48, s[4:5]
	global_load_dwordx4 v[36:39], v49, s[4:5]
	global_load_dwordx4 v[40:43], v50, s[4:5]
	global_load_dwordx4 v[44:47], v51, s[4:5]
	s_add_u32 s4, s4, 0x200
	s_addc_u32 s5, s5, 0
	s_waitcnt vmcnt(8)
	ds_write_b128 v52, v[0:3]
	ds_write_b128 v52, v[4:7] offset:1024
	ds_write_b128 v52, v[8:11] offset:2048
	ds_write_b128 v52, v[12:15] offset:3072
	s_waitcnt lgkmcnt(0)
	ds_read_b64_tr_b16 v[16:17], v55
	ds_read_b64_tr_b16 v[18:19], v55 offset:1024
	ds_read_b64_tr_b16 v[20:21], v55 offset:32
	ds_read_b64_tr_b16 v[22:23], v55 offset:1056
	ds_read_b64_tr_b16 v[24:25], v55 offset:2048
	ds_read_b64_tr_b16 v[26:27], v55 offset:3072
	ds_read_b64_tr_b16 v[28:29], v55 offset:2080
	ds_read_b64_tr_b16 v[30:31], v55 offset:3104
	s_waitcnt lgkmcnt(0)
	global_store_dwordx4 v56, v[16:19], s[6:7]
	global_store_dwordx4 v56, v[20:23], s[6:7] offset:2048
	global_store_dwordx4 v57, v[24:27], s[6:7]
	global_store_dwordx4 v57, v[28:31], s[6:7] offset:2048
	s_add_u32 s6, s6, 0x800000
	s_addc_u32 s7, s7, 0
	global_load_dwordx4 v[0:3], v48, s[4:5]
	global_load_dwordx4 v[4:7], v49, s[4:5]
	global_load_dwordx4 v[8:11], v50, s[4:5]
	global_load_dwordx4 v[12:15], v51, s[4:5]
	s_add_u32 s4, s4, 0x200
	s_addc_u32 s5, s5, 0
	s_waitcnt vmcnt(8)
	ds_write_b128 v52, v[32:35]
	ds_write_b128 v52, v[36:39] offset:1024
	ds_write_b128 v52, v[40:43] offset:2048
	ds_write_b128 v52, v[44:47] offset:3072
	s_waitcnt lgkmcnt(0)
	ds_read_b64_tr_b16 v[16:17], v55
	ds_read_b64_tr_b16 v[18:19], v55 offset:1024
	ds_read_b64_tr_b16 v[20:21], v55 offset:32
	ds_read_b64_tr_b16 v[22:23], v55 offset:1056
	ds_read_b64_tr_b16 v[24:25], v55 offset:2048
	ds_read_b64_tr_b16 v[26:27], v55 offset:3072
	ds_read_b64_tr_b16 v[28:29], v55 offset:2080
	ds_read_b64_tr_b16 v[30:31], v55 offset:3104
	s_waitcnt lgkmcnt(0)
	global_store_dwordx4 v56, v[16:19], s[6:7]
	global_store_dwordx4 v56, v[20:23], s[6:7] offset:2048
	global_store_dwordx4 v57, v[24:27], s[6:7]
	global_store_dwordx4 v57, v[28:31], s[6:7] offset:2048
	s_add_u32 s6, s6, 0x800000
	s_addc_u32 s7, s7, 0
	global_load_dwordx4 v[32:35], v48, s[4:5]
	global_load_dwordx4 v[36:39], v49, s[4:5]
	global_load_dwordx4 v[40:43], v50, s[4:5]
	global_load_dwordx4 v[44:47], v51, s[4:5]
	s_add_u32 s4, s4, 0x200
	s_addc_u32 s5, s5, 0
	s_waitcnt vmcnt(8)
	ds_write_b128 v52, v[0:3]
	ds_write_b128 v52, v[4:7] offset:1024
	ds_write_b128 v52, v[8:11] offset:2048
	ds_write_b128 v52, v[12:15] offset:3072
	s_waitcnt lgkmcnt(0)
	ds_read_b64_tr_b16 v[16:17], v55
	ds_read_b64_tr_b16 v[18:19], v55 offset:1024
	ds_read_b64_tr_b16 v[20:21], v55 offset:32
	ds_read_b64_tr_b16 v[22:23], v55 offset:1056
	ds_read_b64_tr_b16 v[24:25], v55 offset:2048
	ds_read_b64_tr_b16 v[26:27], v55 offset:3072
	ds_read_b64_tr_b16 v[28:29], v55 offset:2080
	ds_read_b64_tr_b16 v[30:31], v55 offset:3104
	s_waitcnt lgkmcnt(0)
	global_store_dwordx4 v56, v[16:19], s[6:7]
	global_store_dwordx4 v56, v[20:23], s[6:7] offset:2048
	global_store_dwordx4 v57, v[24:27], s[6:7]
	global_store_dwordx4 v57, v[28:31], s[6:7] offset:2048
	s_add_u32 s6, s6, 0x800000
	s_addc_u32 s7, s7, 0
	global_load_dwordx4 v[0:3], v48, s[4:5]
	global_load_dwordx4 v[4:7], v49, s[4:5]
	global_load_dwordx4 v[8:11], v50, s[4:5]
	global_load_dwordx4 v[12:15], v51, s[4:5]
	s_add_u32 s4, s4, 0x200
	s_addc_u32 s5, s5, 0
	s_waitcnt vmcnt(8)
	ds_write_b128 v52, v[32:35]
	ds_write_b128 v52, v[36:39] offset:1024
	ds_write_b128 v52, v[40:43] offset:2048
	ds_write_b128 v52, v[44:47] offset:3072
	s_waitcnt lgkmcnt(0)
	ds_read_b64_tr_b16 v[16:17], v55
	ds_read_b64_tr_b16 v[18:19], v55 offset:1024
	ds_read_b64_tr_b16 v[20:21], v55 offset:32
	ds_read_b64_tr_b16 v[22:23], v55 offset:1056
	ds_read_b64_tr_b16 v[24:25], v55 offset:2048
	ds_read_b64_tr_b16 v[26:27], v55 offset:3072
	ds_read_b64_tr_b16 v[28:29], v55 offset:2080
	ds_read_b64_tr_b16 v[30:31], v55 offset:3104
	s_waitcnt lgkmcnt(0)
	global_store_dwordx4 v56, v[16:19], s[6:7]
	global_store_dwordx4 v56, v[20:23], s[6:7] offset:2048
	global_store_dwordx4 v57, v[24:27], s[6:7]
	global_store_dwordx4 v57, v[28:31], s[6:7] offset:2048
	s_add_u32 s6, s6, 0x800000
	s_addc_u32 s7, s7, 0
	global_load_dwordx4 v[32:35], v48, s[4:5]
	global_load_dwordx4 v[36:39], v49, s[4:5]
	global_load_dwordx4 v[40:43], v50, s[4:5]
	global_load_dwordx4 v[44:47], v51, s[4:5]
	s_add_u32 s4, s4, 0x200
	s_addc_u32 s5, s5, 0
	s_waitcnt vmcnt(8)
	ds_write_b128 v52, v[0:3]
	ds_write_b128 v52, v[4:7] offset:1024
	ds_write_b128 v52, v[8:11] offset:2048
	ds_write_b128 v52, v[12:15] offset:3072
	s_waitcnt lgkmcnt(0)
	ds_read_b64_tr_b16 v[16:17], v55
	ds_read_b64_tr_b16 v[18:19], v55 offset:1024
	ds_read_b64_tr_b16 v[20:21], v55 offset:32
	ds_read_b64_tr_b16 v[22:23], v55 offset:1056
	ds_read_b64_tr_b16 v[24:25], v55 offset:2048
	ds_read_b64_tr_b16 v[26:27], v55 offset:3072
	ds_read_b64_tr_b16 v[28:29], v55 offset:2080
	ds_read_b64_tr_b16 v[30:31], v55 offset:3104
	s_waitcnt lgkmcnt(0)
	global_store_dwordx4 v56, v[16:19], s[6:7]
	global_store_dwordx4 v56, v[20:23], s[6:7] offset:2048
	global_store_dwordx4 v57, v[24:27], s[6:7]
	global_store_dwordx4 v57, v[28:31], s[6:7] offset:2048
	s_add_u32 s6, s6, 0x800000
	s_addc_u32 s7, s7, 0
	s_waitcnt vmcnt(4)
	ds_write_b128 v52, v[32:35]
	ds_write_b128 v52, v[36:39] offset:1024
	ds_write_b128 v52, v[40:43] offset:2048
	ds_write_b128 v52, v[44:47] offset:3072
	s_waitcnt lgkmcnt(0)
	ds_read_b64_tr_b16 v[16:17], v55
	ds_read_b64_tr_b16 v[18:19], v55 offset:1024
	ds_read_b64_tr_b16 v[20:21], v55 offset:32
	ds_read_b64_tr_b16 v[22:23], v55 offset:1056
	ds_read_b64_tr_b16 v[24:25], v55 offset:2048
	ds_read_b64_tr_b16 v[26:27], v55 offset:3072
	ds_read_b64_tr_b16 v[28:29], v55 offset:2080
	ds_read_b64_tr_b16 v[30:31], v55 offset:3104
	s_waitcnt lgkmcnt(0)
	global_store_dwordx4 v56, v[16:19], s[6:7]
	global_store_dwordx4 v56, v[20:23], s[6:7] offset:2048
	global_store_dwordx4 v57, v[24:27], s[6:7]
	global_store_dwordx4 v57, v[28:31], s[6:7] offset:2048
	s_add_u32 s6, s6, 0x800000
	s_addc_u32 s7, s7, 0

.LBB0_254:
	s_cmp_lt_i32 s59, 1
	s_cbranch_scc1 .LBB0_360
	s_add_u32 s3, s64, 0
	v_writelane_b32 v254, s90, 11
	s_addc_u32 s6, s65, 0
	s_ashr_i32 s0, s88, 4
	v_writelane_b32 v254, s91, 12
	s_and_b32 s0, s0, -2
	v_writelane_b32 v254, s0, 13
	v_writelane_b32 v254, s88, 14
	s_and_b32 s0, s88, 31
	v_writelane_b32 v254, s0, 15
	s_and_b32 s0, s87, 0xffffffc0
	v_mov_b32_e32 v0, 0x3e4ccccd
	v_writelane_b32 v254, s0, 16
	s_lshl_b32 s0, s0, 2
	v_add_f32_e32 v0, s1, v0
	s_add_i32 s96, s0, 0
	s_add_i32 s0, s89, -4
	s_lshl_b32 s1, s89, 7
	s_lshl_b32 s4, s89, 18
	s_bfe_u32 s7, s87, 0x20006
	s_lshl_b32 s9, s0, 13
	s_and_b32 s1, s1, 0xffffff00
	s_and_b32 s4, s4, 0x40000
	s_lshl_b32 s0, s0, 13
	s_lshr_b32 s8, s87, 8
	s_lshl_b32 s14, s7, 5
	s_add_i32 s96, s96, 0x20200
	s_add_i32 s10, s1, s4
	s_lshl_b32 s11, s89, 13
	s_add_i32 s12, s0, 0x8000
	s_cmpk_lt_u32 s87, 0x100
	s_cselect_b64 s[0:1], -1, 0
	s_and_b64 s[4:5], s[0:1], exec
	s_movk_i32 s5, 0x400
	v_writelane_b32 v254, s89, 17
	s_cselect_b32 s4, s11, s12
	s_cselect_b32 s11, 0x8000, s5
	s_mov_b32 s5, 0x10000
	v_writelane_b32 v254, s87, 18
	s_cselect_b32 s12, s5, 0x800
	s_mov_b32 s5, 0x18000
	s_cselect_b32 s20, 0xc0, 0
	s_cselect_b32 s16, s5, 0xc00
	s_mov_b32 s5, 0x20000
	v_writelane_b32 v254, s20, 19
	s_cselect_b32 s20, 0x80, 0
	s_cselect_b32 s17, s5, 0x1000
	s_mov_b32 s5, 0x28000
	v_writelane_b32 v254, s20, 20
	s_cselect_b32 s20, 64, 0
	s_cselect_b32 s18, s5, 0x1400
	s_mov_b32 s5, 0x30000
	v_writelane_b32 v254, s20, 21
	s_cselect_b32 s19, s5, 0x1800
	s_mov_b32 s5, 0x38000
	s_cselect_b32 s63, s95, s6
	v_writelane_b32 v254, s94, 22
	s_cselect_b32 s5, s5, 0x1c00
	s_cselect_b32 s93, s10, s9
	v_writelane_b32 v254, s95, 23
	s_cselect_b32 s62, s94, s3
	s_add_i32 s97, s4, 0
	s_lshl_b32 s4, s8, 14
	v_writelane_b32 v254, s4, 24
	s_lshl_b32 s4, s7, 15
	s_add_i32 s75, s97, 0x400
	s_add_i32 s68, s97, 0x800
	s_add_i32 s69, s97, 0xc00
	s_add_i32 s78, s97, 0x1000
	s_add_i32 s79, s97, 0x1400
	s_add_i32 s54, s97, 0x1800
	s_add_i32 s55, s97, 0x1c00
	s_lshl_b32 s3, s8, 7
	s_add_i32 s71, s97, 0x10000
	s_add_i32 s92, s97, 0x10400
	s_add_i32 s70, s97, 0x10800
	s_add_i32 s80, s97, 0x10c00
	s_add_i32 s81, s97, 0x11000
	s_add_i32 s50, s97, 0x11400
	s_add_i32 s51, s97, 0x11800
	s_add_i32 s94, s97, 0x11c00
	s_add_i32 s95, s4, 0
	s_cmp_eq_u32 s8, 1
	s_cselect_b64 s[6:7], -1, 0
	v_writelane_b32 v254, s6, 25
	s_lshl_b32 s4, s8, 4
	s_mov_b32 s15, 0
	v_writelane_b32 v254, s7, 26
	v_writelane_b32 v254, s4, 27
	v_writelane_b32 v254, s14, 28
	s_add_i32 s4, s14, 0xffffffa5
	v_writelane_b32 v254, s4, 29
	v_writelane_b32 v254, s5, 30
	s_add_i32 s4, s93, s5
	v_writelane_b32 v254, s4, 31
	v_writelane_b32 v254, s16, 32
	s_add_i32 s4, s93, s16
	v_writelane_b32 v254, s4, 33
	v_writelane_b32 v254, s19, 34
	s_add_i32 s4, s93, s19
	v_writelane_b32 v254, s4, 35
	v_writelane_b32 v254, s12, 36
	s_add_i32 s4, s93, s12
	v_writelane_b32 v254, s4, 37
	v_writelane_b32 v254, s18, 38
	s_add_i32 s4, s93, s18
	v_writelane_b32 v254, s4, 39
	v_writelane_b32 v254, s11, 40
	s_add_i32 s4, s93, s11
	v_writelane_b32 v254, s4, 41
	v_writelane_b32 v254, s17, 42
	s_add_i32 s4, s93, s17
	v_xor_b32_e32 v210, 0x80000000, v0
	v_writelane_b32 v254, s4, 43
	s_lshl_b32 s14, s3, 1
	v_mov_b32_e32 v212, v210
	v_mov_b32_e32 v213, v210
	v_mov_b32_e32 v1, 0
	s_mov_b32 s74, 0x41000000
	v_mov_b32_e32 v214, 0x3727c5ac
	v_mov_b32_e32 v215, 0x41b17218
	v_mov_b32_e32 v216, 0xff800000
	v_writelane_b32 v254, s14, 44
	s_mov_b32 s72, s15
	s_nop 0
	v_writelane_b32 v254, s15, 45
	s_branch .LBB0_257

.LBB0_265:
	s_or_b64 exec, exec, s[6:7]
	v_ashrrev_i32_e32 v0, 4, v211
	v_lshlrev_b32_e32 v2, 13, v0
	v_bitop3_b32 v3, v211, v0, 15 bitop3:0x6c
	v_ashrrev_i32_e32 v218, 5, v211
	v_lshl_add_u32 v2, v3, 4, v2
	v_lshlrev_b32_e32 v0, 3, v0
	v_bfe_u32 v3, v211, 2, 2
	s_and_b32 s5, s72, 1
	s_sub_i32 s6, 0x7f, s3
	v_and_or_b32 v0, v0, 8, v3
	v_lshlrev_b32_e32 v3, 6, v218
	s_cmp_eq_u32 s5, 0
	v_lshl_add_u32 v0, v0, 13, v3
	v_lshlrev_b32_e32 v6, 4, v211
	s_cselect_b32 s5, s6, s3
	v_and_or_b32 v0, v6, 48, v0
	s_lshl_b32 s90, s4, 9
	v_lshlrev_b32_e32 v0, 4, v211
	s_lshl_b32 s8, s4, 23
	s_cmp_lg_u64 s[0:1], 0
	s_cselect_b32 s90, s90, s8
	v_cndmask_b32_e64 v7, v0, v2, s[0:1]
	s_add_i32 s7, s90, s93
	v_add_u32_e32 v0, s7, v7
	s_mov_b32 s8, m0
	s_mov_b32 m0, s97
	s_nop 0
	global_load_lds_dwordx4 v0, s[62:63]
	s_mov_b32 m0, s8
	s_lshl_b32 s6, s5, 7
	v_readlane_b32 s8, v254, 21
	v_readlane_b32 s3, v254, 28
	v_and_b32_e32 v217, 31, v211
	v_xor_b32_e32 v8, s8, v7
	v_add_u32_e32 v2, s7, v8
	v_readlane_b32 s8, v254, 40
	s_or_b32 s3, s6, s3
	s_lshl_b32 s82, s4, 8
	v_add_u32_e32 v3, s8, v2
	s_mov_b32 s8, m0
	s_mov_b32 m0, s75
	s_nop 0
	global_load_lds_dwordx4 v3, s[62:63]
	s_mov_b32 m0, s8
	s_ashr_i32 s83, s82, 31
	v_readlane_b32 s8, v254, 20
	v_readlane_b32 s4, v254, 24
	v_mov_b32_e32 v14, v1
	v_xor_b32_e32 v9, s8, v7
	v_add_u32_e32 v3, s7, v9
	v_readlane_b32 s8, v254, 36
	v_mov_b32_e32 v15, v1
	v_add_u32_e32 v231, s93, v7
	v_add_u32_e32 v4, s8, v3
	s_mov_b32 s8, m0
	s_mov_b32 m0, s68
	s_nop 0
	global_load_lds_dwordx4 v4, s[62:63]
	s_mov_b32 m0, s8
	v_mov_b32_e32 v11, v1
	v_readlane_b32 s8, v254, 19
	v_mov_b32_e32 v12, v1
	v_mov_b32_e32 v13, v1
	v_xor_b32_e32 v10, s8, v7
	v_add_u32_e32 v4, s7, v10
	v_readlane_b32 s7, v254, 32
	v_readlane_b32 s8, v254, 44
	v_readlane_b32 s9, v254, 45
	v_add_u32_e32 v5, s7, v4
	s_mov_b32 s7, m0
	s_mov_b32 m0, s69
	s_nop 0
	global_load_lds_dwordx4 v5, s[62:63]
	s_mov_b32 m0, s7
	s_mov_b32 s91, 0
	v_readlane_b32 s7, v254, 42
	s_lshl_b32 s88, s5, 1
	s_lshr_b32 s89, s3, 6
	v_add_u32_e32 v0, s7, v0
	s_mov_b32 s7, m0
	s_mov_b32 m0, s78
	s_nop 0
	global_load_lds_dwordx4 v0, s[62:63]
	s_mov_b32 m0, s7
	s_add_i32 s73, s3, 0xffffff10
	v_readlane_b32 s7, v254, 38
	v_cmp_gt_u32_e64 s[36:37], 32, v211
	v_lshl_add_u32 v220, v217, 2, s96
	v_add_u32_e32 v0, s7, v2
	s_mov_b32 s7, m0
	s_mov_b32 m0, s79
	s_nop 0
	global_load_lds_dwordx4 v0, s[62:63]
	s_mov_b32 m0, s7
	v_lshlrev_b32_e32 v219, 4, v218
	v_readlane_b32 s7, v254, 34
	v_mov_b32_e32 v233, 0xf149f2ca
	v_mov_b32_e32 v232, 0
	v_add_u32_e32 v0, s7, v3
	s_mov_b32 s7, m0
	s_mov_b32 m0, s54
	s_nop 0
	global_load_lds_dwordx4 v0, s[62:63]
	s_mov_b32 m0, s7
	s_mov_b32 s58, 0
	v_readlane_b32 s7, v254, 30
	s_nop 1
	v_add_u32_e32 v0, s7, v4
	s_mov_b32 s7, m0
	s_mov_b32 m0, s55
	s_nop 0
	global_load_lds_dwordx4 v0, s[62:63]
	s_mov_b32 m0, s7
	v_and_b32_e32 v0, 15, v211
	v_or_b32_e32 v0, s3, v0
	v_lshlrev_b32_e32 v0, 13, v0
	v_lshl_add_u64 v[2:3], s[42:43], 0, v[0:1]
	v_lshl_add_u64 v[2:3], s[82:83], 1, v[2:3]
	v_lshrrev_b32_e32 v4, 4, v211
	v_lshlrev_b32_e32 v4, 3, v4
	v_lshl_add_u64 v[2:3], v[2:3], 0, s[8:9]
	v_ashrrev_i32_e32 v5, 31, v4
	v_lshl_add_u64 v[2:3], v[4:5], 1, v[2:3]
	s_mov_b32 s8, 0x20000
	s_mov_b32 s9, 0
	v_lshl_add_u64 v[4:5], v[2:3], 0, s[8:9]
	global_load_dwordx4 v[178:181], v[2:3], off
	global_load_dwordx4 v[182:185], v[2:3], off offset:64
	global_load_dwordx4 v[186:189], v[2:3], off offset:128
	global_load_dwordx4 v[190:193], v[2:3], off offset:192
	global_load_dwordx4 v[194:197], v[4:5], off
	global_load_dwordx4 v[198:201], v[4:5], off offset:64
	global_load_dwordx4 v[202:205], v[4:5], off offset:128
	global_load_dwordx4 v[206:209], v[4:5], off offset:192
	v_lshlrev_b32_e32 v2, 3, v211
	v_and_b32_e32 v3, 0xc0, v6
	v_lshlrev_b32_e32 v4, 1, v211
	v_and_or_b32 v3, v2, 24, v3
	v_and_b32_e32 v4, 32, v4
	v_and_b32_e32 v2, 0x100, v2
	v_or3_b32 v2, v3, v4, v2
	v_lshl_or_b32 v3, v217, 8, s4
	s_add_i32 s4, 0, 0x8000
	v_add_u32_e32 v222, s4, v2
	v_readlane_b32 s4, v254, 29
	s_add_i32 s4, s4, s6
	v_bitop3_b32 v0, v211, v218, 15 bitop3:0x6c
	v_add_u32_e32 v2, s4, v217
	v_readlane_b32 s4, v254, 31
	v_lshl_add_u32 v221, v0, 4, v3
	v_lshlrev_b32_e32 v0, 2, v218
	v_add_u32_e32 v224, s4, v10
	v_readlane_b32 s4, v254, 33
	v_sub_u32_e32 v223, v2, v0
	v_mov_b32_e32 v0, v1
	v_add_u32_e32 v225, s4, v10
	v_readlane_b32 s4, v254, 35
	v_mov_b32_e32 v2, v1
	v_mov_b32_e32 v3, v1
	v_add_u32_e32 v226, s4, v9
	v_readlane_b32 s4, v254, 37
	v_mov_b32_e32 v4, v1
	v_mov_b32_e32 v5, v1
	v_add_u32_e32 v227, s4, v9
	v_readlane_b32 s4, v254, 39
	v_mov_b32_e32 v6, v1
	v_mov_b32_e32 v9, v1
	v_add_u32_e32 v228, s4, v8
	v_readlane_b32 s4, v254, 41
	v_mov_b32_e32 v10, v1
	s_nop 0
	v_add_u32_e32 v229, s4, v8
	v_readlane_b32 s4, v254, 43
	v_mov_b32_e32 v8, v1
	s_nop 0
	v_add_u32_e32 v230, s4, v7
	v_mov_b32_e32 v7, v1
	v_mov_b64_e32 v[128:129], v[14:15]
	v_mov_b64_e32 v[112:113], v[14:15]
	v_mov_b64_e32 v[96:97], v[14:15]
	v_mov_b64_e32 v[80:81], v[14:15]
	v_mov_b64_e32 v[64:65], v[14:15]
	v_mov_b64_e32 v[48:49], v[14:15]
	v_mov_b64_e32 v[32:33], v[14:15]
	v_mov_b64_e32 v[126:127], v[12:13]
	v_mov_b64_e32 v[124:125], v[10:11]
	v_mov_b64_e32 v[122:123], v[8:9]
	v_mov_b64_e32 v[120:121], v[6:7]
	v_mov_b64_e32 v[118:119], v[4:5]
	v_mov_b64_e32 v[116:117], v[2:3]
	v_mov_b64_e32 v[114:115], v[0:1]
	v_mov_b64_e32 v[110:111], v[12:13]
	v_mov_b64_e32 v[108:109], v[10:11]
	v_mov_b64_e32 v[106:107], v[8:9]
	v_mov_b64_e32 v[104:105], v[6:7]
	v_mov_b64_e32 v[102:103], v[4:5]
	v_mov_b64_e32 v[100:101], v[2:3]
	v_mov_b64_e32 v[98:99], v[0:1]
	v_mov_b64_e32 v[94:95], v[12:13]
	v_mov_b64_e32 v[92:93], v[10:11]
	v_mov_b64_e32 v[90:91], v[8:9]
	v_mov_b64_e32 v[88:89], v[6:7]
	v_mov_b64_e32 v[86:87], v[4:5]
	v_mov_b64_e32 v[84:85], v[2:3]
	v_mov_b64_e32 v[82:83], v[0:1]
	v_mov_b64_e32 v[78:79], v[12:13]
	v_mov_b64_e32 v[76:77], v[10:11]
	v_mov_b64_e32 v[74:75], v[8:9]
	v_mov_b64_e32 v[72:73], v[6:7]
	v_mov_b64_e32 v[70:71], v[4:5]
	v_mov_b64_e32 v[68:69], v[2:3]
	v_mov_b64_e32 v[66:67], v[0:1]
	v_mov_b64_e32 v[62:63], v[12:13]
	v_mov_b64_e32 v[60:61], v[10:11]
	v_mov_b64_e32 v[58:59], v[8:9]
	v_mov_b64_e32 v[56:57], v[6:7]
	v_mov_b64_e32 v[54:55], v[4:5]
	v_mov_b64_e32 v[52:53], v[2:3]
	v_mov_b64_e32 v[50:51], v[0:1]
	v_mov_b64_e32 v[46:47], v[12:13]
	v_mov_b64_e32 v[44:45], v[10:11]
	v_mov_b64_e32 v[42:43], v[8:9]
	v_mov_b64_e32 v[40:41], v[6:7]
	v_mov_b64_e32 v[38:39], v[4:5]
	v_mov_b64_e32 v[36:37], v[2:3]
	v_mov_b64_e32 v[34:35], v[0:1]
	v_mov_b64_e32 v[30:31], v[12:13]
	v_mov_b64_e32 v[28:29], v[10:11]
	v_mov_b64_e32 v[26:27], v[8:9]
	v_mov_b64_e32 v[24:25], v[6:7]
	v_mov_b64_e32 v[22:23], v[4:5]
	v_mov_b64_e32 v[20:21], v[2:3]
	v_mov_b64_e32 v[18:19], v[0:1]
	v_mov_b64_e32 v[16:17], v[14:15]
	v_mov_b64_e32 v[14:15], v[12:13]
	v_mov_b64_e32 v[12:13], v[10:11]
	v_mov_b64_e32 v[10:11], v[8:9]
	v_mov_b64_e32 v[8:9], v[6:7]
	v_mov_b64_e32 v[6:7], v[4:5]
	v_mov_b64_e32 v[4:5], v[2:3]
	v_mov_b64_e32 v[2:3], v[0:1]
	s_branch .Lat_entry
.Lat_entry:
	s_mov_b32 s92, m0
	s_add_i32 s71, s97, 0x10000
	s_mov_b32 s70, 0
	s_movk_i32 s81, 0x7f
	s_mov_b32 s80, 0x20000
	s_cmp_lg_u64 s[0:1], 0
	s_mov_b32 s100, 0x8000
	s_cselect_b32 s100, 0x80000, s100
	s_add_i32 s51, s90, s100
	s_add_u32 s50, s62, s51
	s_addc_u32 s51, s63, 0
	s_mov_b32 s84, 1
	s_mov_b32 s94, 0xff800000
	v_mov_b32_e32 v246, 0
	v_mov_b32_e32 v247, 0
	v_mov_b32_e32 v248, 0
	v_mov_b32_e32 v249, 0
	v_mov_b32_e32 v250, 0
	v_mov_b32_e32 v251, 0
	v_mov_b32_e32 v252, 0
	v_mov_b32_e32 v253, 0
	v_readlane_b32 s4, v254, 24
	v_and_b32_e32 v234, 15, v211
	v_lshrrev_b32_e32 v235, 4, v211
	v_xor_b32_e32 v236, v234, v235
	v_lshlrev_b32_e32 v236, 4, v236
	v_lshl_add_u32 v236, v234, 8, v236
	v_add_u32_e32 v221, s4, v236
	v_lshlrev_b32_e32 v237, 2, v235
	v_sub_u32_e32 v237, v234, v237
	v_add_u32_e32 v223, s3, v237
	v_and_b32_e32 v237, 7, v234
	v_lshrrev_b32_e32 v238, 3, v234
	v_xor_b32_e32 v237, v237, v238
	v_xor_b32_e32 v237, v235, v237
	v_lshlrev_b32_e32 v237, 4, v237
	v_lshl_add_u32 v237, v234, 7, v237
	v_add_u32_e32 v222, 0x8000, v237
	v_mov_b32_e32 v243, v233
	v_mov_b32_e32 v244, 0
	v_xor_b32_e32 v234, s70, v221
	v_xor_b32_e32 v235, 64, v234
	v_xor_b32_e32 v236, 0x80, v234
	v_xor_b32_e32 v237, 0xc0, v234
	s_lshl_b64 s[98:99], s[82:83], 1
	s_add_u32 s98, s48, s98
	s_addc_u32 s99, s49, s99
	v_readlane_b32 s4, v254, 27
	s_nop 1
	v_add_u32_e32 v245, s4, v218
	v_add_u32_e32 v245, s3, v245
	v_lshlrev_b32_e32 v245, 13, v245
	v_lshl_add_u32 v245, v217, 4, v245
.Lat_loop:
	s_waitcnt vmcnt(0) lgkmcnt(0)
	s_barrier
	s_cmp_gt_u32 s58, s89
	s_cbranch_scc1 .Lat_inactive
	ds_read_b128 v[162:165], v234
	ds_read_b128 v[166:169], v235
	ds_read_b128 v[170:173], v236
	ds_read_b128 v[174:177], v237
	v_add_u32_e32 v242, s70, v222
	v_xor_b32_e32 v243, 64, v242
	s_add_i32 m0, s71, 0x0
	s_nop 0
	global_load_lds_dwordx4 v231, s[50:51]
	s_add_i32 m0, s71, 0x400
	s_nop 0
	global_load_lds_dwordx4 v229, s[50:51]
	s_waitcnt lgkmcnt(2)
	v_mfma_f32_16x16x32_bf16 v[130:133], v[162:165], v[178:181], v[246:249]
	v_mfma_f32_16x16x32_bf16 v[146:149], v[162:165], v[194:197], v[250:253]
	ds_read_b128 v[162:165], v234 offset:4096
	v_mfma_f32_16x16x32_bf16 v[130:133], v[166:169], v[182:185], v[130:133]
	s_add_i32 m0, s71, 0x800
	v_mfma_f32_16x16x32_bf16 v[146:149], v[166:169], v[198:201], v[146:149]
	ds_read_b128 v[166:169], v235 offset:4096
	global_load_lds_dwordx4 v227, s[50:51]
	s_waitcnt lgkmcnt(2)
	v_mfma_f32_16x16x32_bf16 v[130:133], v[170:173], v[186:189], v[130:133]
	v_mfma_f32_16x16x32_bf16 v[146:149], v[170:173], v[202:205], v[146:149]
	ds_read_b128 v[170:173], v236 offset:4096
	v_mfma_f32_16x16x32_bf16 v[130:133], v[174:177], v[190:193], v[130:133]
	s_add_i32 m0, s71, 0xc00
	v_mfma_f32_16x16x32_bf16 v[146:149], v[174:177], v[206:209], v[146:149]
	ds_read_b128 v[174:177], v237 offset:4096
	global_load_lds_dwordx4 v225, s[50:51]
	s_waitcnt lgkmcnt(2)
	v_mfma_f32_16x16x32_bf16 v[134:137], v[162:165], v[178:181], v[246:249]
	v_mfma_f32_16x16x32_bf16 v[150:153], v[162:165], v[194:197], v[250:253]
	ds_read_b128 v[162:165], v234 offset:8192
	v_mfma_f32_16x16x32_bf16 v[134:137], v[166:169], v[182:185], v[134:137]
	s_add_i32 m0, s71, 0x1000
	v_mfma_f32_16x16x32_bf16 v[150:153], v[166:169], v[198:201], v[150:153]
	ds_read_b128 v[166:169], v235 offset:8192
	global_load_lds_dwordx4 v230, s[50:51]
	s_waitcnt lgkmcnt(2)
	v_mfma_f32_16x16x32_bf16 v[134:137], v[170:173], v[186:189], v[134:137]
	v_mfma_f32_16x16x32_bf16 v[150:153], v[170:173], v[202:205], v[150:153]
	ds_read_b128 v[170:173], v236 offset:8192
	v_mfma_f32_16x16x32_bf16 v[134:137], v[174:177], v[190:193], v[134:137]
	s_add_i32 m0, s71, 0x1400
	v_mfma_f32_16x16x32_bf16 v[150:153], v[174:177], v[206:209], v[150:153]
	ds_read_b128 v[174:177], v237 offset:8192
	global_load_lds_dwordx4 v228, s[50:51]
	s_waitcnt lgkmcnt(2)
	v_mfma_f32_16x16x32_bf16 v[138:141], v[162:165], v[178:181], v[246:249]
	v_mfma_f32_16x16x32_bf16 v[154:157], v[162:165], v[194:197], v[250:253]
	ds_read_b128 v[162:165], v234 offset:12288
	v_mfma_f32_16x16x32_bf16 v[138:141], v[166:169], v[182:185], v[138:141]
	s_add_i32 m0, s71, 0x1800
	v_mfma_f32_16x16x32_bf16 v[154:157], v[166:169], v[198:201], v[154:157]
	ds_read_b128 v[166:169], v235 offset:12288
	global_load_lds_dwordx4 v226, s[50:51]
	s_waitcnt lgkmcnt(2)
	v_mfma_f32_16x16x32_bf16 v[138:141], v[170:173], v[186:189], v[138:141]
	v_mfma_f32_16x16x32_bf16 v[154:157], v[170:173], v[202:205], v[154:157]
	ds_read_b128 v[170:173], v236 offset:12288
	v_mfma_f32_16x16x32_bf16 v[138:141], v[174:177], v[190:193], v[138:141]
	s_add_i32 m0, s71, 0x1c00
	v_mfma_f32_16x16x32_bf16 v[154:157], v[174:177], v[206:209], v[154:157]
	ds_read_b128 v[174:177], v237 offset:12288
	global_load_lds_dwordx4 v224, s[50:51]
	s_waitcnt lgkmcnt(2)
	v_mfma_f32_16x16x32_bf16 v[142:145], v[162:165], v[178:181], v[246:249]
	v_mfma_f32_16x16x32_bf16 v[158:161], v[162:165], v[194:197], v[250:253]
	ds_read_b128 v[162:165], v242
	v_mfma_f32_16x16x32_bf16 v[142:145], v[166:169], v[182:185], v[142:145]
	v_mfma_f32_16x16x32_bf16 v[158:161], v[166:169], v[198:201], v[158:161]
	ds_read_b128 v[166:169], v243
	s_waitcnt lgkmcnt(2)
	v_mfma_f32_16x16x32_bf16 v[142:145], v[170:173], v[186:189], v[142:145]
	v_mfma_f32_16x16x32_bf16 v[158:161], v[170:173], v[202:205], v[158:161]
	ds_read_b128 v[170:173], v242 offset:2048
	v_mfma_f32_16x16x32_bf16 v[142:145], v[174:177], v[190:193], v[142:145]
	v_mfma_f32_16x16x32_bf16 v[158:161], v[174:177], v[206:209], v[158:161]
	ds_read_b128 v[174:177], v243 offset:2048

.Lat_exp_a:
	v_exp_f32_e32 v130, v130
	v_exp_f32_e32 v131, v131
	v_exp_f32_e32 v132, v132
	v_add_f32_e32 v0, v130, v131
	v_exp_f32_e32 v133, v133
	v_add_f32_e32 v0, v0, v132
	v_exp_f32_e32 v134, v134
	v_add_f32_e32 v0, v0, v133
	v_exp_f32_e32 v135, v135
	v_add_f32_e32 v0, v0, v134
	v_exp_f32_e32 v136, v136
	v_add_f32_e32 v0, v0, v135
	v_exp_f32_e32 v137, v137
	v_add_f32_e32 v0, v0, v136
	v_exp_f32_e32 v138, v138
	v_add_f32_e32 v0, v0, v137
	v_exp_f32_e32 v139, v139
	v_add_f32_e32 v0, v0, v138
	v_exp_f32_e32 v140, v140
	v_add_f32_e32 v0, v0, v139
	v_exp_f32_e32 v141, v141
	v_add_f32_e32 v0, v0, v140
	v_exp_f32_e32 v142, v142
	v_add_f32_e32 v0, v0, v141
	v_exp_f32_e32 v143, v143
	v_add_f32_e32 v0, v0, v142
	v_exp_f32_e32 v144, v144
	v_add_f32_e32 v0, v0, v143
	v_exp_f32_e32 v145, v145
	v_add_f32_e32 v0, v0, v144
	v_exp_f32_e32 v146, v146
	v_exp_f32_e32 v147, v147
	v_exp_f32_e32 v148, v148
	v_add_f32_e32 v233, v146, v147
	v_exp_f32_e32 v149, v149
	v_add_f32_e32 v233, v233, v148
	v_exp_f32_e32 v150, v150
	v_add_f32_e32 v233, v233, v149
	v_exp_f32_e32 v151, v151
	v_add_f32_e32 v233, v233, v150
	v_exp_f32_e32 v152, v152
	v_add_f32_e32 v233, v233, v151
	v_exp_f32_e32 v153, v153
	v_add_f32_e32 v233, v233, v152
	v_exp_f32_e32 v154, v154
	v_add_f32_e32 v233, v233, v153
	v_exp_f32_e32 v155, v155
	v_add_f32_e32 v233, v233, v154
	v_exp_f32_e32 v156, v156
	v_add_f32_e32 v233, v233, v155
	v_exp_f32_e32 v157, v157
	v_add_f32_e32 v233, v233, v156
	v_exp_f32_e32 v158, v158
	v_add_f32_e32 v233, v233, v157
	v_exp_f32_e32 v159, v159
	v_add_f32_e32 v233, v233, v158
	v_exp_f32_e32 v160, v160
	v_add_f32_e32 v233, v233, v159
	v_exp_f32_e32 v161, v161
	v_add_f32_e32 v233, v233, v160
	v_add_f32_e32 v0, v0, v145
	v_add_f32_e32 v233, v233, v161
	v_max_f32_e32 v238, v0, v233
	v_cmp_ge_f32_e32 vcc, 0x43800000, v238
	s_cmp_eq_u64 vcc, exec
	s_cbranch_scc0 .Lat_redo_a
	v_add_f32_e32 v232, v232, v0
	v_cvt_pk_bf16_f32 v130, v130, v131
	v_cvt_pk_bf16_f32 v131, v132, v133
	v_cvt_pk_bf16_f32 v132, v134, v135
	v_cvt_pk_bf16_f32 v133, v136, v137
	v_cvt_pk_bf16_f32 v134, v138, v139
	v_cvt_pk_bf16_f32 v135, v140, v141
	v_cvt_pk_bf16_f32 v136, v142, v143
	v_cvt_pk_bf16_f32 v137, v144, v145
	v_add_f32_e32 v244, v244, v233
	v_cvt_pk_bf16_f32 v146, v146, v147
	v_cvt_pk_bf16_f32 v147, v148, v149
	v_cvt_pk_bf16_f32 v148, v150, v151
	v_cvt_pk_bf16_f32 v149, v152, v153
	v_cvt_pk_bf16_f32 v150, v154, v155
	v_cvt_pk_bf16_f32 v151, v156, v157
	v_cvt_pk_bf16_f32 v152, v158, v159
	v_cvt_pk_bf16_f32 v153, v160, v161
	s_waitcnt lgkmcnt(2)
	v_mfma_f32_16x16x32_bf16 v[114:117], v[162:165], v[130:133], v[114:117]
	v_mfma_f32_16x16x32_bf16 v[122:125], v[162:165], v[146:149], v[122:125]
	ds_read_b128 v[162:165], v242 offset:4096
	v_mfma_f32_16x16x32_bf16 v[114:117], v[166:169], v[134:137], v[114:117]
	v_mfma_f32_16x16x32_bf16 v[122:125], v[166:169], v[150:153], v[122:125]
	ds_read_b128 v[166:169], v243 offset:4096
	s_waitcnt lgkmcnt(2)
	v_mfma_f32_16x16x32_bf16 v[118:121], v[170:173], v[130:133], v[118:121]
	v_mfma_f32_16x16x32_bf16 v[126:129], v[170:173], v[146:149], v[126:129]
	ds_read_b128 v[170:173], v242 offset:6144
	v_mfma_f32_16x16x32_bf16 v[118:121], v[174:177], v[134:137], v[118:121]
	v_mfma_f32_16x16x32_bf16 v[126:129], v[174:177], v[150:153], v[126:129]
	ds_read_b128 v[174:177], v243 offset:6144
	s_waitcnt lgkmcnt(2)
	v_mfma_f32_16x16x32_bf16 v[98:101], v[162:165], v[130:133], v[98:101]
	v_mfma_f32_16x16x32_bf16 v[106:109], v[162:165], v[146:149], v[106:109]
	ds_read_b128 v[162:165], v242 offset:8192
	v_mfma_f32_16x16x32_bf16 v[98:101], v[166:169], v[134:137], v[98:101]
	v_mfma_f32_16x16x32_bf16 v[106:109], v[166:169], v[150:153], v[106:109]
	ds_read_b128 v[166:169], v243 offset:8192
	s_waitcnt lgkmcnt(2)
	v_mfma_f32_16x16x32_bf16 v[102:105], v[170:173], v[130:133], v[102:105]
	v_mfma_f32_16x16x32_bf16 v[110:113], v[170:173], v[146:149], v[110:113]
	ds_read_b128 v[170:173], v242 offset:10240
	v_mfma_f32_16x16x32_bf16 v[102:105], v[174:177], v[134:137], v[102:105]
	v_mfma_f32_16x16x32_bf16 v[110:113], v[174:177], v[150:153], v[110:113]
	ds_read_b128 v[174:177], v243 offset:10240
	s_waitcnt lgkmcnt(2)
	v_mfma_f32_16x16x32_bf16 v[82:85], v[162:165], v[130:133], v[82:85]
	v_mfma_f32_16x16x32_bf16 v[90:93], v[162:165], v[146:149], v[90:93]
	ds_read_b128 v[162:165], v242 offset:12288
	v_mfma_f32_16x16x32_bf16 v[82:85], v[166:169], v[134:137], v[82:85]
	v_mfma_f32_16x16x32_bf16 v[90:93], v[166:169], v[150:153], v[90:93]
	ds_read_b128 v[166:169], v243 offset:12288
	s_waitcnt lgkmcnt(2)
	v_mfma_f32_16x16x32_bf16 v[86:89], v[170:173], v[130:133], v[86:89]
	v_mfma_f32_16x16x32_bf16 v[94:97], v[170:173], v[146:149], v[94:97]
	ds_read_b128 v[170:173], v242 offset:14336
	v_mfma_f32_16x16x32_bf16 v[86:89], v[174:177], v[134:137], v[86:89]
	v_mfma_f32_16x16x32_bf16 v[94:97], v[174:177], v[150:153], v[94:97]
	ds_read_b128 v[174:177], v243 offset:14336
	s_waitcnt lgkmcnt(2)
	v_mfma_f32_16x16x32_bf16 v[66:69], v[162:165], v[130:133], v[66:69]
	v_mfma_f32_16x16x32_bf16 v[74:77], v[162:165], v[146:149], v[74:77]
	ds_read_b128 v[162:165], v242 offset:16384
	v_mfma_f32_16x16x32_bf16 v[66:69], v[166:169], v[134:137], v[66:69]
	v_mfma_f32_16x16x32_bf16 v[74:77], v[166:169], v[150:153], v[74:77]
	ds_read_b128 v[166:169], v243 offset:16384
	s_waitcnt lgkmcnt(2)
	v_mfma_f32_16x16x32_bf16 v[70:73], v[170:173], v[130:133], v[70:73]
	v_mfma_f32_16x16x32_bf16 v[78:81], v[170:173], v[146:149], v[78:81]
	ds_read_b128 v[170:173], v242 offset:18432
	v_mfma_f32_16x16x32_bf16 v[70:73], v[174:177], v[134:137], v[70:73]
	v_mfma_f32_16x16x32_bf16 v[78:81], v[174:177], v[150:153], v[78:81]
	ds_read_b128 v[174:177], v243 offset:18432
	s_waitcnt lgkmcnt(2)
	v_mfma_f32_16x16x32_bf16 v[50:53], v[162:165], v[130:133], v[50:53]
	v_mfma_f32_16x16x32_bf16 v[58:61], v[162:165], v[146:149], v[58:61]
	ds_read_b128 v[162:165], v242 offset:20480
	v_mfma_f32_16x16x32_bf16 v[50:53], v[166:169], v[134:137], v[50:53]
	v_mfma_f32_16x16x32_bf16 v[58:61], v[166:169], v[150:153], v[58:61]
	ds_read_b128 v[166:169], v243 offset:20480
	s_waitcnt lgkmcnt(2)
	v_mfma_f32_16x16x32_bf16 v[54:57], v[170:173], v[130:133], v[54:57]
	v_mfma_f32_16x16x32_bf16 v[62:65], v[170:173], v[146:149], v[62:65]
	ds_read_b128 v[170:173], v242 offset:22528
	v_mfma_f32_16x16x32_bf16 v[54:57], v[174:177], v[134:137], v[54:57]
	v_mfma_f32_16x16x32_bf16 v[62:65], v[174:177], v[150:153], v[62:65]
	ds_read_b128 v[174:177], v243 offset:22528
	s_waitcnt lgkmcnt(2)
	v_mfma_f32_16x16x32_bf16 v[34:37], v[162:165], v[130:133], v[34:37]
	v_mfma_f32_16x16x32_bf16 v[42:45], v[162:165], v[146:149], v[42:45]
	ds_read_b128 v[162:165], v242 offset:24576
	v_mfma_f32_16x16x32_bf16 v[34:37], v[166:169], v[134:137], v[34:37]
	v_mfma_f32_16x16x32_bf16 v[42:45], v[166:169], v[150:153], v[42:45]
	ds_read_b128 v[166:169], v243 offset:24576
	s_waitcnt lgkmcnt(2)
	v_mfma_f32_16x16x32_bf16 v[38:41], v[170:173], v[130:133], v[38:41]
	v_mfma_f32_16x16x32_bf16 v[46:49], v[170:173], v[146:149], v[46:49]
	ds_read_b128 v[170:173], v242 offset:26624
	v_mfma_f32_16x16x32_bf16 v[38:41], v[174:177], v[134:137], v[38:41]
	v_mfma_f32_16x16x32_bf16 v[46:49], v[174:177], v[150:153], v[46:49]
	ds_read_b128 v[174:177], v243 offset:26624
	s_waitcnt lgkmcnt(2)
	v_mfma_f32_16x16x32_bf16 v[18:21], v[162:165], v[130:133], v[18:21]
	v_mfma_f32_16x16x32_bf16 v[26:29], v[162:165], v[146:149], v[26:29]
	ds_read_b128 v[162:165], v242 offset:28672
	v_mfma_f32_16x16x32_bf16 v[18:21], v[166:169], v[134:137], v[18:21]
	v_mfma_f32_16x16x32_bf16 v[26:29], v[166:169], v[150:153], v[26:29]
	ds_read_b128 v[166:169], v243 offset:28672
	s_waitcnt lgkmcnt(2)
	v_mfma_f32_16x16x32_bf16 v[22:25], v[170:173], v[130:133], v[22:25]
	v_mfma_f32_16x16x32_bf16 v[30:33], v[170:173], v[146:149], v[30:33]
	ds_read_b128 v[170:173], v242 offset:30720
	v_mfma_f32_16x16x32_bf16 v[22:25], v[174:177], v[134:137], v[22:25]
	v_mfma_f32_16x16x32_bf16 v[30:33], v[174:177], v[150:153], v[30:33]
	ds_read_b128 v[174:177], v243 offset:30720
	s_waitcnt lgkmcnt(2)
	v_mfma_f32_16x16x32_bf16 v[2:5], v[162:165], v[130:133], v[2:5]
	v_mfma_f32_16x16x32_bf16 v[10:13], v[162:165], v[146:149], v[10:13]
	v_mfma_f32_16x16x32_bf16 v[2:5], v[166:169], v[134:137], v[2:5]
	v_mfma_f32_16x16x32_bf16 v[10:13], v[166:169], v[150:153], v[10:13]
	s_waitcnt lgkmcnt(0)
	v_mfma_f32_16x16x32_bf16 v[6:9], v[170:173], v[130:133], v[6:9]
	v_mfma_f32_16x16x32_bf16 v[14:17], v[170:173], v[146:149], v[14:17]
	v_mfma_f32_16x16x32_bf16 v[6:9], v[174:177], v[134:137], v[6:9]
	v_mfma_f32_16x16x32_bf16 v[14:17], v[174:177], v[150:153], v[14:17]
	s_xor_b32 s4, s70, 0x10000
	v_xor_b32_e32 v234, s4, v221
	v_xor_b32_e32 v235, 64, v234
	v_xor_b32_e32 v236, 0x80, v234
	v_xor_b32_e32 v237, 0xc0, v234
	s_branch .Lat_end_a

.Lat_end_a:
.Lat_next:
	s_add_i32 s58, s58, 1
	s_xor_b32 s70, s70, 0x10000
	s_xor_b32 s71, s71, 0x10000
	v_add_u32_e32 v223, 0xffffffc0, v223
	s_addk_i32 s91, 0x40
	s_add_u32 s50, s50, s100
	s_addc_u32 s51, s51, 0
	s_mov_b32 s94, 0
	s_cmp_le_u32 s58, s88
	s_cbranch_scc1 .Lat_loop
	s_waitcnt vmcnt(0) lgkmcnt(0)
	s_barrier
	s_add_i32 m0, s71, 0x0
	s_nop 0
	global_load_lds_dwordx4 v245, s[98:99]
	s_add_i32 m0, s71, 0x400
	v_add_u32_e32 v245, 0x4000, v245
	global_load_lds_dwordx4 v245, s[98:99]
	s_add_i32 m0, s71, 0x800
	v_add_u32_e32 v245, 0x4000, v245
	global_load_lds_dwordx4 v245, s[98:99]
	s_add_i32 m0, s71, 0xc00
	v_add_u32_e32 v245, 0x4000, v245
	global_load_lds_dwordx4 v245, s[98:99]
	s_add_i32 m0, s71, 0x1000
	v_add_u32_e32 v245, 0x4000, v245
	global_load_lds_dwordx4 v245, s[98:99]
	s_add_i32 m0, s71, 0x1400
	v_add_u32_e32 v245, 0x4000, v245
	global_load_lds_dwordx4 v245, s[98:99]
	s_add_i32 m0, s71, 0x1800
	v_add_u32_e32 v245, 0x4000, v245
	global_load_lds_dwordx4 v245, s[98:99]
	s_add_i32 m0, s71, 0x1c00
	v_add_u32_e32 v245, 0x4000, v245
	global_load_lds_dwordx4 v245, s[98:99]
	s_cmp_gt_u32 s58, s89
	s_cbranch_scc1 .Lat_done
	ds_read_b128 v[162:165], v234
	ds_read_b128 v[166:169], v235
	ds_read_b128 v[170:173], v236
	ds_read_b128 v[174:177], v237
	v_add_u32_e32 v242, s70, v222
	v_xor_b32_e32 v243, 64, v242
	s_waitcnt lgkmcnt(2)
	v_mfma_f32_16x16x32_bf16 v[130:133], v[162:165], v[178:181], v[246:249]
	v_mfma_f32_16x16x32_bf16 v[146:149], v[162:165], v[194:197], v[250:253]
	ds_read_b128 v[162:165], v234 offset:4096
	v_mfma_f32_16x16x32_bf16 v[130:133], v[166:169], v[182:185], v[130:133]
	v_mfma_f32_16x16x32_bf16 v[146:149], v[166:169], v[198:201], v[146:149]
	ds_read_b128 v[166:169], v235 offset:4096
	s_waitcnt lgkmcnt(2)
	v_mfma_f32_16x16x32_bf16 v[130:133], v[170:173], v[186:189], v[130:133]
	v_mfma_f32_16x16x32_bf16 v[146:149], v[170:173], v[202:205], v[146:149]
	ds_read_b128 v[170:173], v236 offset:4096
	v_mfma_f32_16x16x32_bf16 v[130:133], v[174:177], v[190:193], v[130:133]
	v_mfma_f32_16x16x32_bf16 v[146:149], v[174:177], v[206:209], v[146:149]
	ds_read_b128 v[174:177], v237 offset:4096
	s_waitcnt lgkmcnt(2)
	v_mfma_f32_16x16x32_bf16 v[134:137], v[162:165], v[178:181], v[246:249]
	v_mfma_f32_16x16x32_bf16 v[150:153], v[162:165], v[194:197], v[250:253]
	ds_read_b128 v[162:165], v234 offset:8192
	v_mfma_f32_16x16x32_bf16 v[134:137], v[166:169], v[182:185], v[134:137]
	v_mfma_f32_16x16x32_bf16 v[150:153], v[166:169], v[198:201], v[150:153]
	ds_read_b128 v[166:169], v235 offset:8192
	s_waitcnt lgkmcnt(2)
	v_mfma_f32_16x16x32_bf16 v[134:137], v[170:173], v[186:189], v[134:137]
	v_mfma_f32_16x16x32_bf16 v[150:153], v[170:173], v[202:205], v[150:153]
	ds_read_b128 v[170:173], v236 offset:8192
	v_mfma_f32_16x16x32_bf16 v[134:137], v[174:177], v[190:193], v[134:137]
	v_mfma_f32_16x16x32_bf16 v[150:153], v[174:177], v[206:209], v[150:153]
	ds_read_b128 v[174:177], v237 offset:8192
	s_waitcnt lgkmcnt(2)
	v_mfma_f32_16x16x32_bf16 v[138:141], v[162:165], v[178:181], v[246:249]
	v_mfma_f32_16x16x32_bf16 v[154:157], v[162:165], v[194:197], v[250:253]
	ds_read_b128 v[162:165], v234 offset:12288
	v_mfma_f32_16x16x32_bf16 v[138:141], v[166:169], v[182:185], v[138:141]
	v_mfma_f32_16x16x32_bf16 v[154:157], v[166:169], v[198:201], v[154:157]
	ds_read_b128 v[166:169], v235 offset:12288
	s_waitcnt lgkmcnt(2)
	v_mfma_f32_16x16x32_bf16 v[138:141], v[170:173], v[186:189], v[138:141]
	v_mfma_f32_16x16x32_bf16 v[154:157], v[170:173], v[202:205], v[154:157]
	ds_read_b128 v[170:173], v236 offset:12288
	v_mfma_f32_16x16x32_bf16 v[138:141], v[174:177], v[190:193], v[138:141]
	v_mfma_f32_16x16x32_bf16 v[154:157], v[174:177], v[206:209], v[154:157]
	ds_read_b128 v[174:177], v237 offset:12288
	s_waitcnt lgkmcnt(2)
	v_mfma_f32_16x16x32_bf16 v[142:145], v[162:165], v[178:181], v[246:249]
	v_mfma_f32_16x16x32_bf16 v[158:161], v[162:165], v[194:197], v[250:253]
	ds_read_b128 v[162:165], v242
	v_mfma_f32_16x16x32_bf16 v[142:145], v[166:169], v[182:185], v[142:145]
	v_mfma_f32_16x16x32_bf16 v[158:161], v[166:169], v[198:201], v[158:161]
	ds_read_b128 v[166:169], v243
	s_waitcnt lgkmcnt(2)
	v_mfma_f32_16x16x32_bf16 v[142:145], v[170:173], v[186:189], v[142:145]
	v_mfma_f32_16x16x32_bf16 v[158:161], v[170:173], v[202:205], v[158:161]
	ds_read_b128 v[170:173], v242 offset:2048
	v_mfma_f32_16x16x32_bf16 v[142:145], v[174:177], v[190:193], v[142:145]
	v_mfma_f32_16x16x32_bf16 v[158:161], v[174:177], v[206:209], v[158:161]
	ds_read_b128 v[174:177], v243 offset:2048

	.amdhsa_kernel _Z10hybrid_fwd4Args
		.amdhsa_group_segment_fixed_size 0
		.amdhsa_private_segment_fixed_size 0
		.amdhsa_kernarg_size 376
		.amdhsa_user_sgpr_count 2
		.amdhsa_user_sgpr_dispatch_ptr 0
		.amdhsa_user_sgpr_queue_ptr 0
		.amdhsa_user_sgpr_kernarg_segment_ptr 1
		.amdhsa_user_sgpr_dispatch_id 0
		.amdhsa_user_sgpr_kernarg_preload_length 0
		.amdhsa_user_sgpr_kernarg_preload_offset 0
		.amdhsa_user_sgpr_private_segment_size 0
		.amdhsa_uses_dynamic_stack 0
		.amdhsa_enable_private_segment 0
		.amdhsa_system_sgpr_workgroup_id_x 1
		.amdhsa_system_sgpr_workgroup_id_y 0
		.amdhsa_system_sgpr_workgroup_id_z 0
		.amdhsa_system_sgpr_workgroup_info 0
		.amdhsa_system_vgpr_workitem_id 0
		.amdhsa_next_free_vgpr 255
		.amdhsa_next_free_sgpr 102
		.amdhsa_accum_offset 256
		.amdhsa_reserve_vcc 1
		.amdhsa_float_round_mode_32 0
		.amdhsa_float_round_mode_16_64 0
		.amdhsa_float_denorm_mode_32 3
		.amdhsa_float_denorm_mode_16_64 3
		.amdhsa_dx10_clamp 1
		.amdhsa_ieee_mode 1
		.amdhsa_fp16_overflow 0
		.amdhsa_tg_split 0
		.amdhsa_exception_fp_ieee_invalid_op 0
		.amdhsa_exception_fp_denorm_src 0
		.amdhsa_exception_fp_ieee_div_zero 0
		.amdhsa_exception_fp_ieee_overflow 0
		.amdhsa_exception_fp_ieee_underflow 0
		.amdhsa_exception_fp_ieee_inexact 0
		.amdhsa_exception_int_div_zero 0
	.end_amdhsa_kernel

amdhsa.kernels:
  - .agpr_count:     0
    .args:
      - .offset:         0
        .size:           120
        .value_kind:     by_value
      - .offset:         120
        .size:           4
        .value_kind:     hidden_block_count_x
      - .offset:         124
        .size:           4
        .value_kind:     hidden_block_count_y
      - .offset:         128
        .size:           4
        .value_kind:     hidden_block_count_z
      - .offset:         132
        .size:           2
        .value_kind:     hidden_group_size_x
      - .offset:         134
        .size:           2
        .value_kind:     hidden_group_size_y
      - .offset:         136
        .size:           2
        .value_kind:     hidden_group_size_z
      - .offset:         138
        .size:           2
        .value_kind:     hidden_remainder_x
      - .offset:         140
        .size:           2
        .value_kind:     hidden_remainder_y
      - .offset:         142
        .size:           2
        .value_kind:     hidden_remainder_z
      - .offset:         160
        .size:           8
        .value_kind:     hidden_global_offset_x
      - .offset:         168
        .size:           8
        .value_kind:     hidden_global_offset_y
      - .offset:         176
        .size:           8
        .value_kind:     hidden_global_offset_z
      - .offset:         184
        .size:           2
        .value_kind:     hidden_grid_dims
      - .offset:         240
        .size:           4
        .value_kind:     hidden_dynamic_lds_size
    .group_segment_fixed_size: 0
    .kernarg_segment_align: 8
    .kernarg_segment_size: 376
    .language:       OpenCL C
    .language_version:
      - 2
      - 0
    .max_flat_workgroup_size: 512
    .name:           _Z10hybrid_fwd4Args
    .private_segment_fixed_size: 0
    .sgpr_count:     108
    .sgpr_spill_count: 46
    .symbol:         _Z10hybrid_fwd4Args.kd
    .uniform_work_group_size: 1
    .uses_dynamic_stack: false
    .vgpr_count:     255
    .vgpr_spill_count: 0
    .wavefront_size: 64
